# v12 plus nt on the layer-1 FFN weight stores of P7 (far consumer)
# baseline (speedup 1.0000x reference)
; __device__ __forceinline__ unsigned cvt_pk_bf16(float lo, float hi) { f32x2_t f = {lo, hi}; bf16x2_t r = __builtin_convertvector(f, bf16x2_t); return __builtin_bit_cast(unsigned, r); }
; #define LAS __attribute__((address_space(3)))
; #define LDS_WAIT() asm volatile("s_waitcnt lgkmcnt(0)" ::: "memory")
; template <int MODE>
; __device__ __forceinline__ void transpose_weight(const float* W, int K, int N, bf16_t* WT, LAS float* scr, int gw, int NGW, int lane, const float* gk = nullptr) {
;     ...
;         for (int i = 0; i < 32; ++i) { const int kk = 2 * i + (lane >> 5); scr[kk * 33 + (lane & 31)] = cur[i]; }
;         LDS_WAIT(); asm volatile("" ::: "memory");
; #pragma unroll
;         for (int j = 0; j < 4; ++j) { const int n = (lane >> 3) + 8 * j; const LAS float* sp = scr + (8 * c) * 33 + n;
;             u32x4 o; o.x = cvt_pk_bf16(sp[0 * 33] * gc0[0], sp[1 * 33] * gc0[1]); o.y = cvt_pk_bf16(sp[2 * 33] * gc0[2], sp[3 * 33] * gc0[3]);
;             o.z = cvt_pk_bf16(sp[4 * 33] * gc1[0], sp[5 * 33] * gc1[1]); o.w = cvt_pk_bf16(sp[6 * 33] * gc1[2], sp[7 * 33] * gc1[3]);
;             *(u32x4*)(WT + (size_t)(drow + n) * K + k0 + 8 * c) = o; }
;         LDS_WAIT(); asm volatile("" ::: "memory");
; #pragma unroll
;         for (int i = 0; i < 32; ++i) cur[i] = nxt[i];
;         gc0 = gn0; gc1 = gn1; it = itn;
.Ltw_join_8:
	ds_write2_b32 v93, v95, v96 offset1:66
	ds_write2_b32 v93, v97, v98 offset0:132 offset1:198
	v_add_u32_e32 v95, 0x400, v93
	ds_write2_b32 v95, v99, v100 offset0:8 offset1:74
	ds_write2_b32 v95, v101, v102 offset0:140 offset1:206
	v_add_u32_e32 v95, 0x800, v93
	ds_write2_b32 v95, v103, v104 offset0:16 offset1:82
	ds_write2_b32 v95, v105, v106 offset0:148 offset1:214
	v_add_u32_e32 v95, 0xc00, v93
	ds_write2_b32 v95, v107, v108 offset0:24 offset1:90
	ds_write2_b32 v95, v109, v110 offset0:156 offset1:222
	v_add_u32_e32 v95, 0x1000, v93
	ds_write2_b32 v95, v127, v136 offset0:32 offset1:98
	ds_write2_b32 v95, v137, v138 offset0:164 offset1:230
	v_add_u32_e32 v95, 0x1400, v93
	ds_write2_b32 v95, v139, v140 offset0:40 offset1:106
	ds_write2_b32 v95, v141, v142 offset0:172 offset1:238
	v_add_u32_e32 v95, 0x1800, v93
	ds_write2_b32 v95, v151, v152 offset0:48 offset1:114
	ds_write2_b32 v95, v153, v154 offset0:180 offset1:246
	v_add_u32_e32 v95, 0x1c00, v93
	ds_write2_b32 v95, v155, v156 offset0:56 offset1:122
	ds_write2_b32 v95, v157, v158 offset0:188 offset1:254
	s_waitcnt lgkmcnt(0)
	ds_read2_b32 v[100:101], v94 offset1:8
	ds_read2_b32 v[102:103], v94 offset0:33 offset1:41
	ds_read2_b32 v[106:107], v94 offset0:66 offset1:74
	ds_read2_b32 v[108:109], v94 offset0:99 offset1:107
	s_mul_hi_i32 s20, s28, 0x2e8ba2e9
	ds_read2_b32 v[136:137], v94 offset0:132 offset1:140
	ds_read2_b32 v[138:139], v94 offset0:165 offset1:173
	ds_read2_b32 v[140:141], v94 offset0:198 offset1:206
	ds_read2_b32 v[152:153], v94 offset0:231 offset1:239
	s_lshr_b32 s21, s20, 31
	s_ashr_i32 s20, s20, 5
	s_add_i32 s28, s20, s21
	s_lshl_b32 s20, s28, 6
	s_waitcnt lgkmcnt(7)
	v_mov_b32_e32 v96, v100
	s_waitcnt lgkmcnt(6)
	v_mov_b32_e32 v97, v102
	s_waitcnt lgkmcnt(5)
	v_mov_b32_e32 v98, v106
	s_waitcnt lgkmcnt(4)
	v_mov_b32_e32 v99, v108
	s_ashr_i32 s21, s20, 31
	v_pk_mul_f32 v[96:97], v[4:5], v[96:97]
	v_pk_mul_f32 v[98:99], v[6:7], v[98:99]
	v_lshl_add_u64 v[104:105], s[20:21], 1, v[90:91]
	v_cvt_pk_bf16_f32 v96, v96, v97
	v_cvt_pk_bf16_f32 v97, v98, v99
	s_waitcnt lgkmcnt(3)
	v_mov_b32_e32 v98, v136
	s_waitcnt lgkmcnt(2)
	v_mov_b32_e32 v99, v138
	s_waitcnt lgkmcnt(1)
	v_mov_b32_e32 v154, v140
	s_waitcnt lgkmcnt(0)
	v_mov_b32_e32 v155, v152
	s_mul_i32 s20, s28, 0xffffea00
	v_pk_mul_f32 v[98:99], v[0:1], v[98:99]
	v_pk_mul_f32 v[154:155], v[2:3], v[154:155]
	s_add_i32 s20, s20, s23
	v_cvt_pk_bf16_f32 v98, v98, v99
	v_cvt_pk_bf16_f32 v99, v154, v155
	v_add_u32_e32 v154, s20, v17
	v_ashrrev_i32_e32 v155, 31, v154
	v_lshlrev_b64 v[156:157], 12, v[154:155]
	v_lshl_add_u64 v[156:157], v[104:105], 0, v[156:157]
	v_mov_b32_e32 v102, v101
	v_mov_b32_e32 v108, v107
	global_store_dwordx4 v[156:157], v[96:99], off nt
	v_mov_b32_e32 v138, v137
	v_mov_b32_e32 v152, v141
	v_pk_mul_f32 v[96:97], v[4:5], v[102:103]
	v_pk_mul_f32 v[98:99], v[6:7], v[108:109]
	v_cvt_pk_bf16_f32 v96, v96, v97
	v_cvt_pk_bf16_f32 v97, v98, v99
	v_pk_mul_f32 v[98:99], v[0:1], v[138:139]
	v_pk_mul_f32 v[100:101], v[2:3], v[152:153]
	v_cvt_pk_bf16_f32 v98, v98, v99
	v_cvt_pk_bf16_f32 v99, v100, v101
	v_add_u32_e32 v100, 8, v154
	v_ashrrev_i32_e32 v101, 31, v100
	v_lshlrev_b64 v[100:101], 12, v[100:101]
	v_lshl_add_u64 v[100:101], v[104:105], 0, v[100:101]
	ds_read2_b32 v[102:103], v94 offset0:16 offset1:24
	ds_read2_b32 v[106:107], v94 offset0:49 offset1:57
	global_store_dwordx4 v[100:101], v[96:99], off nt
	ds_read2_b32 v[100:101], v94 offset0:82 offset1:90
	ds_read2_b32 v[108:109], v94 offset0:115 offset1:123
	ds_read2_b32 v[136:137], v94 offset0:148 offset1:156
	ds_read2_b32 v[138:139], v94 offset0:181 offset1:189
	ds_read2_b32 v[140:141], v94 offset0:214 offset1:222
	ds_read2_b32 v[152:153], v94 offset0:247 offset1:255
	s_waitcnt lgkmcnt(7)
	v_mov_b32_e32 v96, v102
	s_waitcnt lgkmcnt(6)
	v_mov_b32_e32 v97, v106
	s_waitcnt lgkmcnt(5)
	v_mov_b32_e32 v98, v100
	s_waitcnt lgkmcnt(4)
	v_mov_b32_e32 v99, v108
	v_pk_mul_f32 v[96:97], v[4:5], v[96:97]
	v_pk_mul_f32 v[98:99], v[6:7], v[98:99]
	v_cvt_pk_bf16_f32 v96, v96, v97
	v_cvt_pk_bf16_f32 v97, v98, v99
	s_waitcnt lgkmcnt(3)
	v_mov_b32_e32 v98, v136
	s_waitcnt lgkmcnt(2)
	v_mov_b32_e32 v99, v138
	v_mov_b32_e32 v106, v103
	v_mov_b32_e32 v108, v101
	v_mov_b32_e32 v138, v137
	v_pk_mul_f32 v[98:99], v[0:1], v[98:99]
	s_waitcnt lgkmcnt(1)
	v_mov_b32_e32 v156, v140
	s_waitcnt lgkmcnt(0)
	v_mov_b32_e32 v157, v152
	v_pk_mul_f32 v[4:5], v[4:5], v[106:107]
	v_pk_mul_f32 v[6:7], v[6:7], v[108:109]
	v_pk_mul_f32 v[0:1], v[0:1], v[138:139]
	v_mov_b32_e32 v152, v141
	v_pk_mul_f32 v[156:157], v[2:3], v[156:157]
	v_cvt_pk_bf16_f32 v4, v4, v5
	v_cvt_pk_bf16_f32 v5, v6, v7
	v_cvt_pk_bf16_f32 v6, v0, v1
	v_pk_mul_f32 v[0:1], v[2:3], v[152:153]
	v_cvt_pk_bf16_f32 v98, v98, v99
	v_cvt_pk_bf16_f32 v99, v156, v157
	v_add_u32_e32 v156, 16, v154
	v_cvt_pk_bf16_f32 v7, v0, v1
	v_add_u32_e32 v0, 24, v154
	v_ashrrev_i32_e32 v157, 31, v156
	v_ashrrev_i32_e32 v1, 31, v0
	v_lshlrev_b64 v[156:157], 12, v[156:157]
	v_lshlrev_b64 v[0:1], 12, v[0:1]
	v_lshl_add_u64 v[156:157], v[104:105], 0, v[156:157]
	v_lshl_add_u64 v[0:1], v[104:105], 0, v[0:1]
	global_store_dwordx4 v[156:157], v[96:99], off nt
	global_store_dwordx4 v[0:1], v[4:7], off nt
	s_waitcnt vmcnt(4)
	s_waitcnt lgkmcnt(0)
	v_mov_b64_e32 v[0:1], v[12:13]
	v_add_u32_e32 v17, s22, v17
	v_mov_b64_e32 v[4:5], v[8:9]
	s_add_i32 s25, s25, s22
	s_andn2_b64 vcc, exec, s[14:15]
	v_mov_b64_e32 v[6:7], v[10:11]
	v_mov_b64_e32 v[2:3], v[14:15]
	s_mov_b32 s28, s27
	v_mov_b32_e32 v95, v118
	v_mov_b32_e32 v96, v117
	v_mov_b32_e32 v97, v116
	v_mov_b32_e32 v98, v115
	v_mov_b32_e32 v99, v114
	v_mov_b32_e32 v100, v113
	v_mov_b32_e32 v101, v112
	v_mov_b32_e32 v102, v111
	v_mov_b32_e32 v103, v126
	v_mov_b32_e32 v104, v125
	v_mov_b32_e32 v105, v124
	v_mov_b32_e32 v106, v123
	v_mov_b32_e32 v107, v122
	v_mov_b32_e32 v108, v121
	v_mov_b32_e32 v109, v120
	v_mov_b32_e32 v110, v119
	v_mov_b32_e32 v127, v135
	v_mov_b32_e32 v136, v134
	v_mov_b32_e32 v137, v133
	v_mov_b32_e32 v138, v132
	v_mov_b32_e32 v139, v131
	v_mov_b32_e32 v140, v130
	v_mov_b32_e32 v141, v129
	v_mov_b32_e32 v142, v128
	v_mov_b32_e32 v151, v150
	v_mov_b32_e32 v152, v149
	v_mov_b32_e32 v153, v148
	v_mov_b32_e32 v154, v147
	v_mov_b32_e32 v155, v146
	v_mov_b32_e32 v156, v145
	v_mov_b32_e32 v157, v144
	v_mov_b32_e32 v158, v143
	s_cbranch_vccz .LBB0_1234

; __device__ __forceinline__ unsigned cvt_pk_bf16(float lo, float hi) { f32x2_t f = {lo, hi}; bf16x2_t r = __builtin_convertvector(f, bf16x2_t); return __builtin_bit_cast(unsigned, r); }
; #define LAS __attribute__((address_space(3)))
; #define LDS_WAIT() asm volatile("s_waitcnt lgkmcnt(0)" ::: "memory")
; template <int MODE>
; __device__ __forceinline__ void transpose_weight(const float* W, int K, int N, bf16_t* WT, LAS float* scr, int gw, int NGW, int lane, const float* gk = nullptr) {
;     ...
;         for (int i = 0; i < 32; ++i) { const int kk = 2 * i + (lane >> 5); scr[kk * 33 + (lane & 31)] = cur[i]; }
;         LDS_WAIT(); asm volatile("" ::: "memory");
; #pragma unroll
;         for (int j = 0; j < 4; ++j) { const int n = (lane >> 3) + 8 * j; const LAS float* sp = scr + (8 * c) * 33 + n;
;             u32x4 o; o.x = cvt_pk_bf16(sp[0 * 33] * gc0[0], sp[1 * 33] * gc0[1]); o.y = cvt_pk_bf16(sp[2 * 33] * gc0[2], sp[3 * 33] * gc0[3]);
;             o.z = cvt_pk_bf16(sp[4 * 33] * gc1[0], sp[5 * 33] * gc1[1]); o.w = cvt_pk_bf16(sp[6 * 33] * gc1[2], sp[7 * 33] * gc1[3]);
;             *(u32x4*)(WT + (size_t)(drow + n) * K + k0 + 8 * c) = o; }
;         LDS_WAIT(); asm volatile("" ::: "memory");
; #pragma unroll
;         for (int i = 0; i < 32; ++i) cur[i] = nxt[i];
;         gc0 = gn0; gc1 = gn1; it = itn;
.Ltw_join_9:
	v_pk_mul_f32 v[58:59], v[4:5], v[58:59]
	v_pk_mul_f32 v[60:61], v[6:7], v[60:61]
	v_lshl_add_u64 v[66:67], s[14:15], 1, v[24:25]
	v_cvt_pk_bf16_f32 v58, v58, v59
	v_cvt_pk_bf16_f32 v59, v60, v61
	s_waitcnt lgkmcnt(3)
	v_mov_b32_e32 v60, v72
	s_waitcnt lgkmcnt(2)
	v_mov_b32_e32 v61, v74
	s_waitcnt lgkmcnt(1)
	v_mov_b32_e32 v80, v76
	s_waitcnt lgkmcnt(0)
	v_mov_b32_e32 v81, v78
	s_mul_i32 s14, s25, 0xffffea00
	v_pk_mul_f32 v[60:61], v[0:1], v[60:61]
	v_pk_mul_f32 v[80:81], v[2:3], v[80:81]
	s_add_i32 s14, s14, s23
	v_cvt_pk_bf16_f32 v60, v60, v61
	v_cvt_pk_bf16_f32 v61, v80, v81
	v_add_u32_e32 v80, s14, v17
	v_ashrrev_i32_e32 v81, 31, v80
	v_lshlrev_b64 v[82:83], 12, v[80:81]
	v_lshl_add_u64 v[82:83], v[66:67], 0, v[82:83]
	v_mov_b32_e32 v64, v63
	v_mov_b32_e32 v70, v69
	global_store_dwordx4 v[82:83], v[58:61], off nt
	v_mov_b32_e32 v74, v73
	v_mov_b32_e32 v78, v77
	v_pk_mul_f32 v[58:59], v[4:5], v[64:65]
	v_pk_mul_f32 v[60:61], v[6:7], v[70:71]
	v_cvt_pk_bf16_f32 v58, v58, v59
	v_cvt_pk_bf16_f32 v59, v60, v61
	v_pk_mul_f32 v[60:61], v[0:1], v[74:75]
	v_pk_mul_f32 v[62:63], v[2:3], v[78:79]
	v_cvt_pk_bf16_f32 v60, v60, v61
	v_cvt_pk_bf16_f32 v61, v62, v63
	v_add_u32_e32 v62, 8, v80
	v_ashrrev_i32_e32 v63, 31, v62
	v_lshlrev_b64 v[62:63], 12, v[62:63]
	v_lshl_add_u64 v[62:63], v[66:67], 0, v[62:63]
	ds_read2_b32 v[64:65], v94 offset0:16 offset1:24
	ds_read2_b32 v[68:69], v94 offset0:49 offset1:57
	global_store_dwordx4 v[62:63], v[58:61], off nt
	ds_read2_b32 v[62:63], v94 offset0:82 offset1:90
	ds_read2_b32 v[70:71], v94 offset0:115 offset1:123
	ds_read2_b32 v[72:73], v94 offset0:148 offset1:156
	ds_read2_b32 v[74:75], v94 offset0:181 offset1:189
	ds_read2_b32 v[76:77], v94 offset0:214 offset1:222
	ds_read2_b32 v[78:79], v94 offset0:247 offset1:255
	s_waitcnt lgkmcnt(7)
	v_mov_b32_e32 v58, v64
	s_waitcnt lgkmcnt(6)
	v_mov_b32_e32 v59, v68
	s_waitcnt lgkmcnt(5)
	v_mov_b32_e32 v60, v62
	s_waitcnt lgkmcnt(4)
	v_mov_b32_e32 v61, v70
	v_pk_mul_f32 v[58:59], v[4:5], v[58:59]
	v_pk_mul_f32 v[60:61], v[6:7], v[60:61]
	v_cvt_pk_bf16_f32 v58, v58, v59
	v_cvt_pk_bf16_f32 v59, v60, v61
	s_waitcnt lgkmcnt(3)
	v_mov_b32_e32 v60, v72
	s_waitcnt lgkmcnt(2)
	v_mov_b32_e32 v61, v74
	v_mov_b32_e32 v68, v65
	v_mov_b32_e32 v70, v63
	v_mov_b32_e32 v74, v73
	v_pk_mul_f32 v[60:61], v[0:1], v[60:61]
	s_waitcnt lgkmcnt(1)
	v_mov_b32_e32 v82, v76
	s_waitcnt lgkmcnt(0)
	v_mov_b32_e32 v83, v78
	v_pk_mul_f32 v[4:5], v[4:5], v[68:69]
	v_pk_mul_f32 v[6:7], v[6:7], v[70:71]
	v_pk_mul_f32 v[0:1], v[0:1], v[74:75]
	v_mov_b32_e32 v78, v77
	v_pk_mul_f32 v[82:83], v[2:3], v[82:83]
	v_cvt_pk_bf16_f32 v4, v4, v5
	v_cvt_pk_bf16_f32 v5, v6, v7
	v_cvt_pk_bf16_f32 v6, v0, v1
	v_pk_mul_f32 v[0:1], v[2:3], v[78:79]
	v_cvt_pk_bf16_f32 v60, v60, v61
	v_cvt_pk_bf16_f32 v61, v82, v83
	v_add_u32_e32 v82, 16, v80
	v_cvt_pk_bf16_f32 v7, v0, v1
	v_add_u32_e32 v0, 24, v80
	v_ashrrev_i32_e32 v83, 31, v82
	v_ashrrev_i32_e32 v1, 31, v0
	v_lshlrev_b64 v[82:83], 12, v[82:83]
	v_lshlrev_b64 v[0:1], 12, v[0:1]
	v_lshl_add_u64 v[82:83], v[66:67], 0, v[82:83]
	v_lshl_add_u64 v[0:1], v[66:67], 0, v[0:1]
	global_store_dwordx4 v[82:83], v[58:61], off nt
	global_store_dwordx4 v[0:1], v[4:7], off nt
	s_waitcnt vmcnt(4)
	s_waitcnt lgkmcnt(0)
	v_mov_b64_e32 v[0:1], v[12:13]
	v_add_u32_e32 v17, s22, v17
	v_mov_b64_e32 v[4:5], v[8:9]
	s_add_i32 s21, s21, s22
	s_andn2_b64 vcc, exec, s[12:13]
	v_mov_b64_e32 v[6:7], v[10:11]
	v_mov_b64_e32 v[2:3], v[14:15]
	s_mov_b32 s25, s24
	v_mov_b32_e32 v82, v33
	v_mov_b32_e32 v83, v32
	v_mov_b32_e32 v84, v30
	v_mov_b32_e32 v85, v29
	v_mov_b32_e32 v86, v28
	v_mov_b32_e32 v87, v27
	v_mov_b32_e32 v88, v26
	v_mov_b32_e32 v89, v21
	v_mov_b32_e32 v66, v41
	v_mov_b32_e32 v67, v40
	v_mov_b32_e32 v68, v39
	v_mov_b32_e32 v69, v38
	v_mov_b32_e32 v70, v37
	v_mov_b32_e32 v71, v36
	v_mov_b32_e32 v72, v35
	v_mov_b32_e32 v73, v34
	v_mov_b32_e32 v58, v49
	v_mov_b32_e32 v59, v48
	v_mov_b32_e32 v60, v47
	v_mov_b32_e32 v61, v46
	v_mov_b32_e32 v62, v45
	v_mov_b32_e32 v63, v44
	v_mov_b32_e32 v64, v43
	v_mov_b32_e32 v65, v42
	v_mov_b32_e32 v74, v57
	v_mov_b32_e32 v75, v56
	v_mov_b32_e32 v76, v55
	v_mov_b32_e32 v77, v54
	v_mov_b32_e32 v78, v53
	v_mov_b32_e32 v79, v52
	v_mov_b32_e32 v80, v51
	v_mov_b32_e32 v81, v50
	s_cbranch_vccz .LBB0_1238

; __device__ __forceinline__ unsigned cvt_pk_bf16(float lo, float hi) { f32x2_t f = {lo, hi}; bf16x2_t r = __builtin_convertvector(f, bf16x2_t); return __builtin_bit_cast(unsigned, r); }
; #define LAS __attribute__((address_space(3)))
; #define LDS_WAIT() asm volatile("s_waitcnt lgkmcnt(0)" ::: "memory")
; template <int MODE>
; __device__ __forceinline__ void transpose_weight(const float* W, int K, int N, bf16_t* WT, LAS float* scr, int gw, int NGW, int lane, const float* gk = nullptr) {
;     ...
; #pragma unroll
;         for (int i = 0; i < 32; ++i) { const int kk = 2 * i + (lane >> 5); scr[kk * 33 + (lane & 31)] = cur[i]; }
;         LDS_WAIT(); asm volatile("" ::: "memory");
; #pragma unroll
;         for (int j = 0; j < 4; ++j) { const int n = (lane >> 3) + 8 * j; const LAS float* sp = scr + (8 * c) * 33 + n;
;             u32x4 o; o.x = cvt_pk_bf16(sp[0 * 33] * gc0[0], sp[1 * 33] * gc0[1]); o.y = cvt_pk_bf16(sp[2 * 33] * gc0[2], sp[3 * 33] * gc0[3]);
;             o.z = cvt_pk_bf16(sp[4 * 33] * gc1[0], sp[5 * 33] * gc1[1]); o.w = cvt_pk_bf16(sp[6 * 33] * gc1[2], sp[7 * 33] * gc1[3]);
;             *(u32x4*)(WT + (size_t)(drow + n) * K + k0 + 8 * c) = o; }
;         LDS_WAIT(); asm volatile("" ::: "memory");
; #pragma unroll
;         for (int i = 0; i < 32; ++i) cur[i] = nxt[i];
;         gc0 = gn0; gc1 = gn1; it = itn;
.Ltw_join_10:
	ds_write2_b32 v8, v47, v48 offset0:188 offset1:254
	s_ashr_i32 s14, s26, 31
	s_waitcnt lgkmcnt(0)
	s_lshr_b32 s14, s14, 26
	s_add_i32 s14, s26, s14
	ds_read2_b32 v[12:13], v94 offset0:33 offset1:41
	ds_read2_b32 v[14:15], v94 offset1:8
	ds_read2_b32 v[18:19], v94 offset0:66 offset1:74
	ds_read2_b32 v[22:23], v94 offset0:99 offset1:107
	ds_read2_b32 v[24:25], v94 offset0:132 offset1:140
	ds_read2_b32 v[26:27], v94 offset0:165 offset1:173
	ds_read2_b32 v[28:29], v94 offset0:198 offset1:206
	ds_read2_b32 v[32:33], v94 offset0:231 offset1:239
	s_lshr_b32 s18, s14, 6
	s_andn2_b32 s14, s14, 63
	s_mul_i32 s18, s18, 0xff500000
	s_ashr_i32 s15, s14, 31
	v_add_u32_e32 v42, s18, v16
	v_lshl_add_u64 v[34:35], s[14:15], 1, v[2:3]
	v_ashrrev_i32_e32 v43, 31, v42
	s_waitcnt lgkmcnt(6)
	v_cvt_pk_bf16_f32 v8, v14, v12
	s_waitcnt lgkmcnt(4)
	v_cvt_pk_bf16_f32 v9, v18, v22
	s_waitcnt lgkmcnt(2)
	v_cvt_pk_bf16_f32 v10, v24, v26
	s_waitcnt lgkmcnt(0)
	v_cvt_pk_bf16_f32 v11, v28, v32
	v_lshl_add_u64 v[44:45], v[42:43], 1, v[34:35]
	global_store_dwordx4 v[44:45], v[8:11], off nt
	v_add_u32_e32 v12, 0xb000, v42
	v_add_u32_e32 v16, s70, v16
	v_cvt_pk_bf16_f32 v8, v15, v13
	v_cvt_pk_bf16_f32 v9, v19, v23
	v_cvt_pk_bf16_f32 v10, v25, v27
	v_cvt_pk_bf16_f32 v11, v29, v33
	ds_read2_b32 v[14:15], v94 offset0:49 offset1:57
	ds_read2_b32 v[18:19], v94 offset0:16 offset1:24
	ds_read2_b32 v[22:23], v94 offset0:82 offset1:90
	ds_read2_b32 v[24:25], v94 offset0:115 offset1:123
	ds_read2_b32 v[26:27], v94 offset0:148 offset1:156
	ds_read2_b32 v[28:29], v94 offset0:181 offset1:189
	ds_read2_b32 v[32:33], v94 offset0:214 offset1:222
	ds_read2_b32 v[44:45], v94 offset0:247 offset1:255
	v_ashrrev_i32_e32 v13, 31, v12
	v_lshl_add_u64 v[12:13], v[12:13], 1, v[34:35]
	global_store_dwordx4 v[12:13], v[8:11], off nt
	v_add_u32_e32 v12, 0x16000, v42
	v_ashrrev_i32_e32 v13, 31, v12
	s_waitcnt lgkmcnt(6)
	v_cvt_pk_bf16_f32 v8, v18, v14
	s_waitcnt lgkmcnt(4)
	v_cvt_pk_bf16_f32 v9, v22, v24
	s_waitcnt lgkmcnt(2)
	v_cvt_pk_bf16_f32 v10, v26, v28
	s_waitcnt lgkmcnt(0)
	v_cvt_pk_bf16_f32 v11, v32, v44
	v_lshl_add_u64 v[12:13], v[12:13], 1, v[34:35]
	global_store_dwordx4 v[12:13], v[8:11], off nt
	v_add_u32_e32 v12, 0x21000, v42
	v_ashrrev_i32_e32 v13, 31, v12
	v_cvt_pk_bf16_f32 v8, v19, v15
	v_cvt_pk_bf16_f32 v9, v23, v25
	v_cvt_pk_bf16_f32 v10, v27, v29
	v_cvt_pk_bf16_f32 v11, v33, v45
	v_lshl_add_u64 v[12:13], v[12:13], 1, v[34:35]
	global_store_dwordx4 v[12:13], v[8:11], off nt
	s_waitcnt vmcnt(4)
	s_waitcnt lgkmcnt(0)
	s_add_i32 s12, s12, s22
	s_andn2_b64 vcc, exec, s[10:11]
	s_mov_b32 s26, s13
	v_mov_b32_e32 v8, v40
	v_mov_b32_e32 v9, v39
	v_mov_b32_e32 v10, v38
	v_mov_b32_e32 v11, v37
	v_mov_b32_e32 v12, v21
	v_mov_b32_e32 v13, v20
	v_mov_b32_e32 v14, v17
	v_mov_b32_e32 v15, v7
	v_mov_b32_e32 v18, v56
	v_mov_b32_e32 v19, v55
	v_mov_b32_e32 v22, v54
	v_mov_b32_e32 v23, v53
	v_mov_b32_e32 v24, v52
	v_mov_b32_e32 v25, v51
	v_mov_b32_e32 v26, v50
	v_mov_b32_e32 v27, v49
	v_mov_b32_e32 v28, v64
	v_mov_b32_e32 v29, v63
	v_mov_b32_e32 v30, v62
	v_mov_b32_e32 v32, v61
	v_mov_b32_e32 v33, v60
	v_mov_b32_e32 v34, v59
	v_mov_b32_e32 v35, v58
	v_mov_b32_e32 v36, v57
	v_mov_b32_e32 v41, v69
	v_mov_b32_e32 v42, v68
	v_mov_b32_e32 v43, v67
	v_mov_b32_e32 v44, v66
	v_mov_b32_e32 v45, v65
	v_mov_b32_e32 v46, v6
	v_mov_b32_e32 v47, v5
	v_mov_b32_e32 v48, v4
	s_cbranch_vccz .LBB0_1242
